# GEMM mainloops: removed the back-to-back s_setprio 0 / s_setprio 1 pairs between the two MFMA blocks of each super-phase
# baseline (speedup 1.0000x reference)
; #define PG8_STAGE(bufoff, gbase, voff) do { _Pragma("unroll") for (int _i = 0; _i < 2; ++_i) \
;         __builtin_amdgcn_global_load_lds((const unsigned*)((const char*)(gbase) + (voff)[_i]), (PG8_LAS unsigned*)(lds + (bufoff) + ldsw + _i * 8192), 16, 0, 0); } while (0)
; #define PG8_LDA(dst, b, h) do { _Pragma("unroll") for (int m = 0; m < 4; ++m) _Pragma("unroll") for (int k = 0; k < 2; ++k) dst[m][k] = *(const PG8_LAS bf16x8*)(lds + PG8_SA(b, h) + aoff + m * 2048 + k * 1024); } while (0)
; #define PG8_LDB(dst, b, h) do { _Pragma("unroll") for (int n = 0; n < 2; ++n) _Pragma("unroll") for (int k = 0; k < 2; ++k) dst[n][k] = *(const PG8_LAS bf16x8*)(lds + PG8_SB(b, h) + boff + n * 2048 + k * 1024); } while (0)
; #define PG8_MMA(ai, bj, At, Bt) do { __builtin_amdgcn_s_setprio(1); _Pragma("unroll") for (int m = 0; m < 4; ++m) _Pragma("unroll") for (int n = 0; n < 2; ++n) _Pragma("unroll") for (int k = 0; k < 2; ++k) \
;         acc[ai][bj][m][n] = __builtin_amdgcn_mfma_f32_16x16x32_bf16(Bt[n][k], At[m][k], acc[ai][bj][m][n], 0, 0, 0); __builtin_amdgcn_s_setprio(0); } while (0)
; #define PG8_WAIT_V(n) asm volatile("s_waitcnt vmcnt(" #n ")" ::: "memory")
; #define PG8_WAIT_L(n) asm volatile("s_waitcnt lgkmcnt(" #n ")" ::: "memory")
; #define PG8_BAR __builtin_amdgcn_s_barrier()
; #define PG8_SCHED __builtin_amdgcn_sched_barrier(0)
; template <class Epi, class Sched, bool ALIGN_EPI = false, bool SP2 = false>
; __device__ __forceinline__ void gemm_phase(PG8_LAS unsigned char* lds, const Gemm g, const Sched& S, const Epi& E) {
;     ...
;             PG8_LDB(B0, 0, 0); PG8_LDB(B1, 0, 1); PG8_SCHED; PG8_LDA(At, 0, 0); PG8_STAGE(PG8_SA(1, 1), a1 + hstep, voffA);
;             PG8_WAIT_V(8); PG8_WAIT_L(0); PG8_BAR; PG8_MMA(0, 0, At, B0); PG8_MMA(0, 1, At, B1); PG8_BAR; PG8_SCHED;
;             PG8_LDA(At, 0, 1); PG8_STAGE(PG8_SB(0, 0), b2, voffB); PG8_STAGE(PG8_SB(0, 1), b2 + hstep, voffB); PG8_STAGE(PG8_SA(0, 0), a2, voffA);
;             PG8_WAIT_V(8); PG8_WAIT_L(0); PG8_BAR; PG8_MMA(1, 0, At, B0); PG8_MMA(1, 1, At, B1); PG8_BAR; PG8_SCHED;
.LBB0_100:
	s_add_u32 s16, s24, 0xfff80080
	s_addc_u32 s17, s25, -1
	s_add_i32 s45, 0, 0x10000
	s_cmp_eq_u32 s44, 28
	s_cselect_b32 s19, s11, s17
	s_cselect_b32 s18, s38, s16
	s_cselect_b32 s17, s9, s41
	s_cselect_b32 s16, s39, s40
	s_add_i32 s48, 0, 0x14000
	v_add_u32_e32 v156, s45, v145
	v_add_u32_e32 v172, s48, v145
	ds_read_b128 v[140:143], v156
	ds_read_b128 v[148:151], v156 offset:1024
	ds_read_b128 v[152:155], v156 offset:2048
	ds_read_b128 v[156:159], v156 offset:3072
	ds_read_b128 v[160:163], v172
	ds_read_b128 v[164:167], v172 offset:1024
	ds_read_b128 v[168:171], v172 offset:2048
	ds_read_b128 v[172:175], v172 offset:3072
	v_lshl_add_u64 v[176:177], s[24:25], 0, v[136:137]
	s_add_i32 m0, s1, 0xc000
	ds_read_b128 v[180:183], v147
	ds_read_b128 v[184:187], v147 offset:1024
	ds_read_b128 v[202:205], v147 offset:2048
	ds_read_b128 v[206:209], v147 offset:3072
	ds_read_b128 v[210:213], v147 offset:4096
	ds_read_b128 v[214:217], v147 offset:5120
	ds_read_b128 v[218:221], v147 offset:6144
	ds_read_b128 v[222:225], v147 offset:7168
	global_load_lds_dwordx4 v[176:177], off
	v_lshl_add_u64 v[176:177], s[24:25], 0, v[138:139]
	s_add_i32 m0, s1, 0xe000
	s_nop 0
	global_load_lds_dwordx4 v[176:177], off
	s_waitcnt vmcnt(8)
	s_waitcnt lgkmcnt(0)
	s_barrier
	s_setprio 1
	s_waitcnt lgkmcnt(0)
	v_mfma_f32_16x16x32_bf16 v[126:129], v[140:143], v[180:183], v[126:129]
	v_mfma_f32_16x16x32_bf16 v[122:125], v[152:155], v[180:183], v[122:125]
	v_mfma_f32_16x16x32_bf16 v[110:113], v[140:143], v[202:205], v[110:113]
	v_mfma_f32_16x16x32_bf16 v[106:109], v[152:155], v[202:205], v[106:109]
	v_mfma_f32_16x16x32_bf16 v[94:97], v[140:143], v[210:213], v[94:97]
	v_mfma_f32_16x16x32_bf16 v[90:93], v[152:155], v[210:213], v[90:93]
	v_mfma_f32_16x16x32_bf16 v[78:81], v[140:143], v[218:221], v[78:81]
	v_mfma_f32_16x16x32_bf16 v[74:77], v[152:155], v[218:221], v[74:77]
	v_mfma_f32_16x16x32_bf16 v[126:129], v[148:151], v[184:187], v[126:129]
	v_mfma_f32_16x16x32_bf16 v[122:125], v[156:159], v[184:187], v[122:125]
	v_mfma_f32_16x16x32_bf16 v[110:113], v[148:151], v[206:209], v[110:113]
	v_mfma_f32_16x16x32_bf16 v[106:109], v[156:159], v[206:209], v[106:109]
	v_mfma_f32_16x16x32_bf16 v[94:97], v[148:151], v[214:217], v[94:97]
	v_mfma_f32_16x16x32_bf16 v[90:93], v[156:159], v[214:217], v[90:93]
	v_mfma_f32_16x16x32_bf16 v[78:81], v[148:151], v[222:225], v[78:81]
	v_mfma_f32_16x16x32_bf16 v[74:77], v[156:159], v[222:225], v[74:77]
	v_mfma_f32_16x16x32_bf16 v[118:121], v[160:163], v[180:183], v[118:121]
	v_mfma_f32_16x16x32_bf16 v[114:117], v[168:171], v[180:183], v[114:117]
	v_mfma_f32_16x16x32_bf16 v[102:105], v[160:163], v[202:205], v[102:105]
	v_mfma_f32_16x16x32_bf16 v[98:101], v[168:171], v[202:205], v[98:101]
	v_mfma_f32_16x16x32_bf16 v[86:89], v[160:163], v[210:213], v[86:89]
	v_mfma_f32_16x16x32_bf16 v[82:85], v[168:171], v[210:213], v[82:85]
	v_mfma_f32_16x16x32_bf16 v[70:73], v[160:163], v[218:221], v[70:73]
	v_mfma_f32_16x16x32_bf16 v[66:69], v[168:171], v[218:221], v[66:69]
	v_mfma_f32_16x16x32_bf16 v[118:121], v[164:167], v[184:187], v[118:121]
	v_mfma_f32_16x16x32_bf16 v[114:117], v[172:175], v[184:187], v[114:117]
	v_mfma_f32_16x16x32_bf16 v[102:105], v[164:167], v[206:209], v[102:105]
	v_mfma_f32_16x16x32_bf16 v[98:101], v[172:175], v[206:209], v[98:101]
	v_mfma_f32_16x16x32_bf16 v[86:89], v[164:167], v[214:217], v[86:89]
	v_mfma_f32_16x16x32_bf16 v[82:85], v[172:175], v[214:217], v[82:85]
	v_mfma_f32_16x16x32_bf16 v[70:73], v[164:167], v[222:225], v[70:73]
	v_mfma_f32_16x16x32_bf16 v[66:69], v[172:175], v[222:225], v[66:69]
	s_setprio 0
	s_barrier
	s_add_i32 s45, s45, s0
	v_lshl_add_u64 v[176:177], s[16:17], 0, v[0:1]
	s_mov_b32 m0, s45
	ds_read_b128 v[180:183], v147 offset:16384
	ds_read_b128 v[184:187], v147 offset:17408
	ds_read_b128 v[202:205], v147 offset:18432
	ds_read_b128 v[206:209], v147 offset:19456
	ds_read_b128 v[210:213], v147 offset:20480
	ds_read_b128 v[214:217], v147 offset:21504
	ds_read_b128 v[218:221], v147 offset:22528
	ds_read_b128 v[222:225], v147 offset:23552
	global_load_lds_dwordx4 v[176:177], off
	s_add_i32 m0, s45, 0x2000
	s_add_u32 s46, s16, 0x80000
	v_lshl_add_u64 v[188:189], s[16:17], 0, v[130:131]
	s_addc_u32 s47, s17, 0
	s_add_i32 s45, s48, s0
	global_load_lds_dwordx4 v[188:189], off
	v_lshl_add_u64 v[226:227], s[46:47], 0, v[0:1]
	s_mov_b32 m0, s45
	v_lshl_add_u64 v[228:229], s[18:19], 0, v[132:133]
	global_load_lds_dwordx4 v[226:227], off
	v_lshl_add_u64 v[226:227], s[46:47], 0, v[130:131]
	s_add_i32 m0, s45, 0x2000
	s_nop 0
	global_load_lds_dwordx4 v[226:227], off
	v_lshl_add_u64 v[226:227], s[18:19], 0, v[134:135]
	s_mov_b32 m0, s1
	s_nop 0
	global_load_lds_dwordx4 v[226:227], off
	s_mov_b32 m0, s14
	s_nop 0
	global_load_lds_dwordx4 v[228:229], off
	s_waitcnt vmcnt(8)
	s_waitcnt lgkmcnt(0)
	s_barrier
; #define PG8_STAGE(bufoff, gbase, voff) do { _Pragma("unroll") for (int _i = 0; _i < 2; ++_i) \
;         __builtin_amdgcn_global_load_lds((const unsigned*)((const char*)(gbase) + (voff)[_i]), (PG8_LAS unsigned*)(lds + (bufoff) + ldsw + _i * 8192), 16, 0, 0); } while (0)
; #define PG8_LDA(dst, b, h) do { _Pragma("unroll") for (int m = 0; m < 4; ++m) _Pragma("unroll") for (int k = 0; k < 2; ++k) dst[m][k] = *(const PG8_LAS bf16x8*)(lds + PG8_SA(b, h) + aoff + m * 2048 + k * 1024); } while (0)
; #define PG8_LDB(dst, b, h) do { _Pragma("unroll") for (int n = 0; n < 2; ++n) _Pragma("unroll") for (int k = 0; k < 2; ++k) dst[n][k] = *(const PG8_LAS bf16x8*)(lds + PG8_SB(b, h) + boff + n * 2048 + k * 1024); } while (0)
; #define PG8_MMA(ai, bj, At, Bt) do { __builtin_amdgcn_s_setprio(1); _Pragma("unroll") for (int m = 0; m < 4; ++m) _Pragma("unroll") for (int n = 0; n < 2; ++n) _Pragma("unroll") for (int k = 0; k < 2; ++k) \
;         acc[ai][bj][m][n] = __builtin_amdgcn_mfma_f32_16x16x32_bf16(Bt[n][k], At[m][k], acc[ai][bj][m][n], 0, 0, 0); __builtin_amdgcn_s_setprio(0); } while (0)
; #define PG8_WAIT_V(n) asm volatile("s_waitcnt vmcnt(" #n ")" ::: "memory")
; #define PG8_WAIT_L(n) asm volatile("s_waitcnt lgkmcnt(" #n ")" ::: "memory")
; #define PG8_BAR __builtin_amdgcn_s_barrier()
; #define PG8_SCHED __builtin_amdgcn_sched_barrier(0)
; template <class Epi, class Sched, bool ALIGN_EPI = false, bool SP2 = false>
; __device__ __forceinline__ void gemm_phase(PG8_LAS unsigned char* lds, const Gemm g, const Sched& S, const Epi& E) {
;     ...
;             PG8_WAIT_V(8); PG8_WAIT_L(0); PG8_BAR; PG8_MMA(1, 0, At, B0); PG8_MMA(1, 1, At, B1); PG8_BAR; PG8_SCHED;
;             PG8_LDB(B0, 1, 0); PG8_LDB(B1, 1, 1); PG8_SCHED; PG8_LDA(At, 1, 0); PG8_STAGE(PG8_SA(0, 1), a2 + hstep, voffA);
;             PG8_WAIT_V(8); PG8_WAIT_L(0); PG8_BAR; PG8_MMA(0, 0, At, B0); PG8_MMA(0, 1, At, B1); PG8_BAR; PG8_SCHED;
;             PG8_LDA(At, 1, 1); PG8_STAGE(PG8_SB(1, 0), b3, voffB); PG8_STAGE(PG8_SB(1, 1), b3 + hstep, voffB); PG8_STAGE(PG8_SA(1, 0), a3, voffA);
	s_setprio 1
	s_waitcnt lgkmcnt(0)
	v_mfma_f32_16x16x32_bf16 v[62:65], v[140:143], v[180:183], v[62:65]
	v_mfma_f32_16x16x32_bf16 v[58:61], v[152:155], v[180:183], v[58:61]
	v_mfma_f32_16x16x32_bf16 v[46:49], v[140:143], v[202:205], v[46:49]
	v_mfma_f32_16x16x32_bf16 v[42:45], v[152:155], v[202:205], v[42:45]
	v_mfma_f32_16x16x32_bf16 v[30:33], v[140:143], v[210:213], v[30:33]
	v_mfma_f32_16x16x32_bf16 v[26:29], v[152:155], v[210:213], v[26:29]
	v_mfma_f32_16x16x32_bf16 v[14:17], v[140:143], v[218:221], v[14:17]
	v_mfma_f32_16x16x32_bf16 v[10:13], v[152:155], v[218:221], v[10:13]
	v_mfma_f32_16x16x32_bf16 v[62:65], v[148:151], v[184:187], v[62:65]
	v_mfma_f32_16x16x32_bf16 v[58:61], v[156:159], v[184:187], v[58:61]
	v_mfma_f32_16x16x32_bf16 v[46:49], v[148:151], v[206:209], v[46:49]
	v_mfma_f32_16x16x32_bf16 v[42:45], v[156:159], v[206:209], v[42:45]
	v_mfma_f32_16x16x32_bf16 v[30:33], v[148:151], v[214:217], v[30:33]
	v_mfma_f32_16x16x32_bf16 v[26:29], v[156:159], v[214:217], v[26:29]
	v_mfma_f32_16x16x32_bf16 v[14:17], v[148:151], v[222:225], v[14:17]
	v_mfma_f32_16x16x32_bf16 v[10:13], v[156:159], v[222:225], v[10:13]
	v_mfma_f32_16x16x32_bf16 v[54:57], v[160:163], v[180:183], v[54:57]
	v_mfma_f32_16x16x32_bf16 v[50:53], v[168:171], v[180:183], v[50:53]
	v_mfma_f32_16x16x32_bf16 v[38:41], v[160:163], v[202:205], v[38:41]
	v_mfma_f32_16x16x32_bf16 v[34:37], v[168:171], v[202:205], v[34:37]
	v_mfma_f32_16x16x32_bf16 v[22:25], v[160:163], v[210:213], v[22:25]
	v_mfma_f32_16x16x32_bf16 v[18:21], v[168:171], v[210:213], v[18:21]
	v_mfma_f32_16x16x32_bf16 v[6:9], v[160:163], v[218:221], v[6:9]
	v_mfma_f32_16x16x32_bf16 v[2:5], v[168:171], v[218:221], v[2:5]
	v_mfma_f32_16x16x32_bf16 v[54:57], v[164:167], v[184:187], v[54:57]
	v_mfma_f32_16x16x32_bf16 v[50:53], v[172:175], v[184:187], v[50:53]
	v_mfma_f32_16x16x32_bf16 v[38:41], v[164:167], v[206:209], v[38:41]
	v_mfma_f32_16x16x32_bf16 v[34:37], v[172:175], v[206:209], v[34:37]
	v_mfma_f32_16x16x32_bf16 v[22:25], v[164:167], v[214:217], v[22:25]
	v_mfma_f32_16x16x32_bf16 v[18:21], v[172:175], v[214:217], v[18:21]
	v_mfma_f32_16x16x32_bf16 v[6:9], v[164:167], v[222:225], v[6:9]
	v_mfma_f32_16x16x32_bf16 v[2:5], v[172:175], v[222:225], v[2:5]
	s_setprio 0
	s_barrier
	s_add_i32 s45, 0, 0x18000
	s_add_i32 s46, 0, 0x1c000
	v_add_u32_e32 v156, s45, v145
	v_add_u32_e32 v172, s46, v145
	ds_read_b128 v[140:143], v156
	ds_read_b128 v[148:151], v156 offset:1024
	ds_read_b128 v[152:155], v156 offset:2048
	ds_read_b128 v[156:159], v156 offset:3072
	ds_read_b128 v[160:163], v172
	ds_read_b128 v[164:167], v172 offset:1024
	ds_read_b128 v[168:171], v172 offset:2048
	ds_read_b128 v[172:175], v172 offset:3072
	s_add_u32 s18, s18, 0x80000
	s_addc_u32 s19, s19, 0
	s_mov_b32 m0, s22
	v_lshl_add_u64 v[230:231], s[18:19], 0, v[134:135]
	ds_read_b128 v[180:183], v147 offset:32768
	ds_read_b128 v[184:187], v147 offset:33792
	ds_read_b128 v[202:205], v147 offset:34816
	ds_read_b128 v[206:209], v147 offset:35840
	ds_read_b128 v[210:213], v147 offset:36864
	ds_read_b128 v[214:217], v147 offset:37888
	ds_read_b128 v[218:221], v147 offset:38912
	ds_read_b128 v[222:225], v147 offset:39936
	global_load_lds_dwordx4 v[230:231], off
	v_lshl_add_u64 v[230:231], s[18:19], 0, v[132:133]
	s_mov_b32 m0, s28
	s_nop 0
	global_load_lds_dwordx4 v[230:231], off
	s_waitcnt vmcnt(8)
	s_waitcnt lgkmcnt(0)
	s_barrier
	s_setprio 1
	s_waitcnt lgkmcnt(0)
	v_mfma_f32_16x16x32_bf16 v[126:129], v[140:143], v[180:183], v[126:129]
	v_mfma_f32_16x16x32_bf16 v[122:125], v[152:155], v[180:183], v[122:125]
	v_mfma_f32_16x16x32_bf16 v[110:113], v[140:143], v[202:205], v[110:113]
	v_mfma_f32_16x16x32_bf16 v[106:109], v[152:155], v[202:205], v[106:109]
	v_mfma_f32_16x16x32_bf16 v[94:97], v[140:143], v[210:213], v[94:97]
	v_mfma_f32_16x16x32_bf16 v[90:93], v[152:155], v[210:213], v[90:93]
	v_mfma_f32_16x16x32_bf16 v[78:81], v[140:143], v[218:221], v[78:81]
	v_mfma_f32_16x16x32_bf16 v[74:77], v[152:155], v[218:221], v[74:77]
	v_mfma_f32_16x16x32_bf16 v[126:129], v[148:151], v[184:187], v[126:129]
	v_mfma_f32_16x16x32_bf16 v[122:125], v[156:159], v[184:187], v[122:125]
	v_mfma_f32_16x16x32_bf16 v[110:113], v[148:151], v[206:209], v[110:113]
	v_mfma_f32_16x16x32_bf16 v[106:109], v[156:159], v[206:209], v[106:109]
	v_mfma_f32_16x16x32_bf16 v[94:97], v[148:151], v[214:217], v[94:97]
	v_mfma_f32_16x16x32_bf16 v[90:93], v[156:159], v[214:217], v[90:93]
	v_mfma_f32_16x16x32_bf16 v[78:81], v[148:151], v[222:225], v[78:81]
	v_mfma_f32_16x16x32_bf16 v[74:77], v[156:159], v[222:225], v[74:77]
	v_mfma_f32_16x16x32_bf16 v[118:121], v[160:163], v[180:183], v[118:121]
	v_mfma_f32_16x16x32_bf16 v[114:117], v[168:171], v[180:183], v[114:117]
	v_mfma_f32_16x16x32_bf16 v[102:105], v[160:163], v[202:205], v[102:105]
	v_mfma_f32_16x16x32_bf16 v[98:101], v[168:171], v[202:205], v[98:101]
	v_mfma_f32_16x16x32_bf16 v[86:89], v[160:163], v[210:213], v[86:89]
	v_mfma_f32_16x16x32_bf16 v[82:85], v[168:171], v[210:213], v[82:85]
	v_mfma_f32_16x16x32_bf16 v[70:73], v[160:163], v[218:221], v[70:73]
	v_mfma_f32_16x16x32_bf16 v[66:69], v[168:171], v[218:221], v[66:69]
	v_mfma_f32_16x16x32_bf16 v[118:121], v[164:167], v[184:187], v[118:121]
	v_mfma_f32_16x16x32_bf16 v[114:117], v[172:175], v[184:187], v[114:117]
	v_mfma_f32_16x16x32_bf16 v[102:105], v[164:167], v[206:209], v[102:105]
	v_mfma_f32_16x16x32_bf16 v[98:101], v[172:175], v[206:209], v[98:101]
	v_mfma_f32_16x16x32_bf16 v[86:89], v[164:167], v[214:217], v[86:89]
	v_mfma_f32_16x16x32_bf16 v[82:85], v[172:175], v[214:217], v[82:85]
	v_mfma_f32_16x16x32_bf16 v[70:73], v[164:167], v[222:225], v[70:73]
	v_mfma_f32_16x16x32_bf16 v[66:69], v[172:175], v[222:225], v[66:69]
	s_setprio 0
	s_barrier
; #define PG8_STAGE(bufoff, gbase, voff) do { _Pragma("unroll") for (int _i = 0; _i < 2; ++_i) \
;         __builtin_amdgcn_global_load_lds((const unsigned*)((const char*)(gbase) + (voff)[_i]), (PG8_LAS unsigned*)(lds + (bufoff) + ldsw + _i * 8192), 16, 0, 0); } while (0)
; #define PG8_LDA(dst, b, h) do { _Pragma("unroll") for (int m = 0; m < 4; ++m) _Pragma("unroll") for (int k = 0; k < 2; ++k) dst[m][k] = *(const PG8_LAS bf16x8*)(lds + PG8_SA(b, h) + aoff + m * 2048 + k * 1024); } while (0)
; #define PG8_MMA(ai, bj, At, Bt) do { __builtin_amdgcn_s_setprio(1); _Pragma("unroll") for (int m = 0; m < 4; ++m) _Pragma("unroll") for (int n = 0; n < 2; ++n) _Pragma("unroll") for (int k = 0; k < 2; ++k) \
;         acc[ai][bj][m][n] = __builtin_amdgcn_mfma_f32_16x16x32_bf16(Bt[n][k], At[m][k], acc[ai][bj][m][n], 0, 0, 0); __builtin_amdgcn_s_setprio(0); } while (0)
; #define PG8_WAIT_V(n) asm volatile("s_waitcnt vmcnt(" #n ")" ::: "memory")
; #define PG8_WAIT_L(n) asm volatile("s_waitcnt lgkmcnt(" #n ")" ::: "memory")
; #define PG8_BAR __builtin_amdgcn_s_barrier()
; #define PG8_SCHED __builtin_amdgcn_sched_barrier(0)
; template <class Epi, class Sched, bool ALIGN_EPI = false, bool SP2 = false>
; __device__ __forceinline__ void gemm_phase(PG8_LAS unsigned char* lds, const Gemm g, const Sched& S, const Epi& E) {
;     ...
;             PG8_WAIT_V(8); PG8_WAIT_L(0); PG8_BAR; PG8_MMA(0, 0, At, B0); PG8_MMA(0, 1, At, B1); PG8_BAR; PG8_SCHED;
;             PG8_LDA(At, 1, 1); PG8_STAGE(PG8_SB(1, 0), b3, voffB); PG8_STAGE(PG8_SB(1, 1), b3 + hstep, voffB); PG8_STAGE(PG8_SA(1, 0), a3, voffA);
;             PG8_WAIT_V(8); PG8_WAIT_L(0); PG8_BAR; PG8_MMA(1, 0, At, B0); PG8_MMA(1, 1, At, B1); PG8_BAR; PG8_SCHED;
;     ...
;         if constexpr (ALIGN_EPI) { if (wr == 0) PG8_BAR; }
	s_add_i32 s18, s45, s0
	v_lshl_add_u64 v[176:177], v[176:177], 0, s[36:37]
	s_mov_b32 m0, s18
	ds_read_b128 v[180:183], v147 offset:49152
	ds_read_b128 v[184:187], v147 offset:50176
	ds_read_b128 v[202:205], v147 offset:51200
	ds_read_b128 v[206:209], v147 offset:52224
	ds_read_b128 v[210:213], v147 offset:53248
	ds_read_b128 v[214:217], v147 offset:54272
	ds_read_b128 v[218:221], v147 offset:55296
	ds_read_b128 v[222:225], v147 offset:56320
	global_load_lds_dwordx4 v[176:177], off
	s_add_i32 m0, s18, 0x2000
	s_add_u32 s16, s16, 0x80080
	v_lshl_add_u64 v[176:177], v[188:189], 0, s[36:37]
	s_addc_u32 s17, s17, 0
	s_add_i32 s18, s46, s0
	global_load_lds_dwordx4 v[176:177], off
	v_lshl_add_u64 v[176:177], s[16:17], 0, v[0:1]
	s_mov_b32 m0, s18
	s_nop 0
	global_load_lds_dwordx4 v[176:177], off
	v_lshl_add_u64 v[176:177], s[16:17], 0, v[130:131]
	s_add_i32 m0, s18, 0x2000
	s_nop 0
	global_load_lds_dwordx4 v[176:177], off
	v_lshl_add_u64 v[176:177], v[226:227], 0, s[36:37]
	s_mov_b32 m0, s29
	s_nop 0
	global_load_lds_dwordx4 v[176:177], off
	v_lshl_add_u64 v[176:177], v[228:229], 0, s[36:37]
	s_mov_b32 m0, s30
	s_nop 0
	global_load_lds_dwordx4 v[176:177], off
	s_waitcnt vmcnt(8)
	s_waitcnt lgkmcnt(0)
	s_barrier
	s_setprio 1
	s_waitcnt lgkmcnt(0)
	v_mfma_f32_16x16x32_bf16 v[62:65], v[140:143], v[180:183], v[62:65]
	v_mfma_f32_16x16x32_bf16 v[58:61], v[152:155], v[180:183], v[58:61]
	v_mfma_f32_16x16x32_bf16 v[46:49], v[140:143], v[202:205], v[46:49]
	v_mfma_f32_16x16x32_bf16 v[42:45], v[152:155], v[202:205], v[42:45]
	v_mfma_f32_16x16x32_bf16 v[30:33], v[140:143], v[210:213], v[30:33]
	v_mfma_f32_16x16x32_bf16 v[26:29], v[152:155], v[210:213], v[26:29]
	v_mfma_f32_16x16x32_bf16 v[14:17], v[140:143], v[218:221], v[14:17]
	v_mfma_f32_16x16x32_bf16 v[10:13], v[152:155], v[218:221], v[10:13]
	v_mfma_f32_16x16x32_bf16 v[62:65], v[148:151], v[184:187], v[62:65]
	v_mfma_f32_16x16x32_bf16 v[58:61], v[156:159], v[184:187], v[58:61]
	v_mfma_f32_16x16x32_bf16 v[46:49], v[148:151], v[206:209], v[46:49]
	v_mfma_f32_16x16x32_bf16 v[42:45], v[156:159], v[206:209], v[42:45]
	v_mfma_f32_16x16x32_bf16 v[30:33], v[148:151], v[214:217], v[30:33]
	v_mfma_f32_16x16x32_bf16 v[26:29], v[156:159], v[214:217], v[26:29]
	v_mfma_f32_16x16x32_bf16 v[14:17], v[148:151], v[222:225], v[14:17]
	v_mfma_f32_16x16x32_bf16 v[10:13], v[156:159], v[222:225], v[10:13]
	v_mfma_f32_16x16x32_bf16 v[54:57], v[160:163], v[180:183], v[54:57]
	v_mfma_f32_16x16x32_bf16 v[50:53], v[168:171], v[180:183], v[50:53]
	v_mfma_f32_16x16x32_bf16 v[38:41], v[160:163], v[202:205], v[38:41]
	v_mfma_f32_16x16x32_bf16 v[34:37], v[168:171], v[202:205], v[34:37]
	v_mfma_f32_16x16x32_bf16 v[22:25], v[160:163], v[210:213], v[22:25]
	v_mfma_f32_16x16x32_bf16 v[18:21], v[168:171], v[210:213], v[18:21]
	v_mfma_f32_16x16x32_bf16 v[6:9], v[160:163], v[218:221], v[6:9]
	v_mfma_f32_16x16x32_bf16 v[2:5], v[168:171], v[218:221], v[2:5]
	v_mfma_f32_16x16x32_bf16 v[54:57], v[164:167], v[184:187], v[54:57]
	v_mfma_f32_16x16x32_bf16 v[50:53], v[172:175], v[184:187], v[50:53]
	v_mfma_f32_16x16x32_bf16 v[38:41], v[164:167], v[206:209], v[38:41]
	v_mfma_f32_16x16x32_bf16 v[34:37], v[172:175], v[206:209], v[34:37]
	v_mfma_f32_16x16x32_bf16 v[22:25], v[164:167], v[214:217], v[22:25]
	v_mfma_f32_16x16x32_bf16 v[18:21], v[172:175], v[214:217], v[18:21]
	v_mfma_f32_16x16x32_bf16 v[6:9], v[164:167], v[222:225], v[6:9]
	v_mfma_f32_16x16x32_bf16 v[2:5], v[172:175], v[222:225], v[2:5]
	s_setprio 0
	s_barrier
	s_add_i32 s44, s44, 2
	s_add_u32 s24, s24, 0x100
	s_addc_u32 s25, s25, 0
	s_add_u32 s40, s40, 0x100
	s_addc_u32 s41, s41, 0
	s_cmp_gt_u32 s44, 29
	s_cbranch_scc0 .LBB0_100
	s_and_b64 vcc, exec, s[6:7]
	s_cbranch_vccz .LBB0_103
	s_barrier

; #define PG8_STAGE(bufoff, gbase, voff) do { _Pragma("unroll") for (int _i = 0; _i < 2; ++_i) \
;         __builtin_amdgcn_global_load_lds((const unsigned*)((const char*)(gbase) + (voff)[_i]), (PG8_LAS unsigned*)(lds + (bufoff) + ldsw + _i * 8192), 16, 0, 0); } while (0)
; #define PG8_LDA(dst, b, h) do { _Pragma("unroll") for (int m = 0; m < 4; ++m) _Pragma("unroll") for (int k = 0; k < 2; ++k) dst[m][k] = *(const PG8_LAS bf16x8*)(lds + PG8_SA(b, h) + aoff + m * 2048 + k * 1024); } while (0)
; #define PG8_LDB(dst, b, h) do { _Pragma("unroll") for (int n = 0; n < 2; ++n) _Pragma("unroll") for (int k = 0; k < 2; ++k) dst[n][k] = *(const PG8_LAS bf16x8*)(lds + PG8_SB(b, h) + boff + n * 2048 + k * 1024); } while (0)
; #define PG8_MMA(ai, bj, At, Bt) do { __builtin_amdgcn_s_setprio(1); _Pragma("unroll") for (int m = 0; m < 4; ++m) _Pragma("unroll") for (int n = 0; n < 2; ++n) _Pragma("unroll") for (int k = 0; k < 2; ++k) \
;         acc[ai][bj][m][n] = __builtin_amdgcn_mfma_f32_16x16x32_bf16(Bt[n][k], At[m][k], acc[ai][bj][m][n], 0, 0, 0); __builtin_amdgcn_s_setprio(0); } while (0)
; #define PG8_WAIT_V(n) asm volatile("s_waitcnt vmcnt(" #n ")" ::: "memory")
; #define PG8_WAIT_L(n) asm volatile("s_waitcnt lgkmcnt(" #n ")" ::: "memory")
; #define PG8_BAR __builtin_amdgcn_s_barrier()
; #define PG8_SCHED __builtin_amdgcn_sched_barrier(0)
; template <class Epi, class Sched, bool ALIGN_EPI = false, bool SP2 = false>
; __device__ __forceinline__ void gemm_phase(PG8_LAS unsigned char* lds, const Gemm g, const Sched& S, const Epi& E) {
;     ...
;             PG8_LDB(B0, 0, 0); PG8_LDB(B1, 0, 1); PG8_SCHED; PG8_LDA(At, 0, 0); PG8_STAGE(PG8_SA(1, 1), a1 + hstep, voffA);
;             PG8_WAIT_V(8); PG8_WAIT_L(0); PG8_BAR; PG8_MMA(0, 0, At, B0); PG8_MMA(0, 1, At, B1); PG8_BAR; PG8_SCHED;
;             PG8_LDA(At, 0, 1); PG8_STAGE(PG8_SB(0, 0), b2, voffB); PG8_STAGE(PG8_SB(0, 1), b2 + hstep, voffB); PG8_STAGE(PG8_SA(0, 0), a2, voffA);
;             PG8_WAIT_V(8); PG8_WAIT_L(0); PG8_BAR; PG8_MMA(1, 0, At, B0); PG8_MMA(1, 1, At, B1); PG8_BAR; PG8_SCHED;
.LBB0_179:
	s_add_i32 s30, s12, 2
	s_add_u32 s31, s10, 0x80
	s_addc_u32 s13, s11, 0
	s_add_i32 s38, 0, 0x10000
	s_cmp_eq_u32 s41, s12
	s_cselect_b32 s13, s7, s13
	s_cselect_b32 s12, s6, s31
	s_cselect_b32 s35, s9, s29
	s_cselect_b32 s34, s8, s28
	s_add_i32 s31, 0, 0x14000
	v_add_u32_e32 v148, s38, v157
	v_add_u32_e32 v168, s31, v157
	ds_read_b128 v[130:133], v148
	ds_read_b128 v[134:137], v148 offset:1024
	ds_read_b128 v[138:141], v148 offset:2048
	ds_read_b128 v[148:151], v148 offset:3072
	ds_read_b128 v[152:155], v168
	ds_read_b128 v[160:163], v168 offset:1024
	ds_read_b128 v[164:167], v168 offset:2048
	ds_read_b128 v[168:171], v168 offset:3072
	v_lshl_add_u64 v[176:177], s[10:11], 0, v[144:145]
	s_add_i32 m0, s1, 0xc000
	ds_read_b128 v[172:175], v159
	ds_read_b128 v[180:183], v159 offset:1024
	ds_read_b128 v[184:187], v159 offset:2048
	ds_read_b128 v[202:205], v159 offset:3072
	ds_read_b128 v[206:209], v159 offset:4096
	ds_read_b128 v[210:213], v159 offset:5120
	ds_read_b128 v[214:217], v159 offset:6144
	ds_read_b128 v[218:221], v159 offset:7168
	global_load_lds_dwordx4 v[176:177], off
	v_lshl_add_u64 v[176:177], s[10:11], 0, v[146:147]
	s_add_i32 m0, s1, 0xe000
	s_nop 0
	global_load_lds_dwordx4 v[176:177], off
	s_waitcnt vmcnt(8)
	s_waitcnt lgkmcnt(0)
	s_barrier
	s_setprio 1
	s_waitcnt lgkmcnt(0)
	v_mfma_f32_16x16x32_bf16 v[126:129], v[130:133], v[172:175], v[126:129]
	v_mfma_f32_16x16x32_bf16 v[122:125], v[138:141], v[172:175], v[122:125]
	v_mfma_f32_16x16x32_bf16 v[118:121], v[130:133], v[184:187], v[118:121]
	v_mfma_f32_16x16x32_bf16 v[106:109], v[138:141], v[184:187], v[106:109]
	v_mfma_f32_16x16x32_bf16 v[102:105], v[130:133], v[206:209], v[102:105]
	v_mfma_f32_16x16x32_bf16 v[90:93], v[138:141], v[206:209], v[90:93]
	v_mfma_f32_16x16x32_bf16 v[86:89], v[130:133], v[214:217], v[86:89]
	v_mfma_f32_16x16x32_bf16 v[74:77], v[138:141], v[214:217], v[74:77]
	v_mfma_f32_16x16x32_bf16 v[126:129], v[134:137], v[180:183], v[126:129]
	v_mfma_f32_16x16x32_bf16 v[122:125], v[148:151], v[180:183], v[122:125]
	v_mfma_f32_16x16x32_bf16 v[118:121], v[134:137], v[202:205], v[118:121]
	v_mfma_f32_16x16x32_bf16 v[106:109], v[148:151], v[202:205], v[106:109]
	v_mfma_f32_16x16x32_bf16 v[102:105], v[134:137], v[210:213], v[102:105]
	v_mfma_f32_16x16x32_bf16 v[90:93], v[148:151], v[210:213], v[90:93]
	v_mfma_f32_16x16x32_bf16 v[86:89], v[134:137], v[218:221], v[86:89]
	v_mfma_f32_16x16x32_bf16 v[74:77], v[148:151], v[218:221], v[74:77]
	v_mfma_f32_16x16x32_bf16 v[114:117], v[152:155], v[172:175], v[114:117]
	v_mfma_f32_16x16x32_bf16 v[110:113], v[164:167], v[172:175], v[110:113]
	v_mfma_f32_16x16x32_bf16 v[98:101], v[152:155], v[184:187], v[98:101]
	v_mfma_f32_16x16x32_bf16 v[94:97], v[164:167], v[184:187], v[94:97]
	v_mfma_f32_16x16x32_bf16 v[82:85], v[152:155], v[206:209], v[82:85]
	v_mfma_f32_16x16x32_bf16 v[78:81], v[164:167], v[206:209], v[78:81]
	v_mfma_f32_16x16x32_bf16 v[70:73], v[152:155], v[214:217], v[70:73]
	v_mfma_f32_16x16x32_bf16 v[66:69], v[164:167], v[214:217], v[66:69]
	v_mfma_f32_16x16x32_bf16 v[114:117], v[160:163], v[180:183], v[114:117]
	v_mfma_f32_16x16x32_bf16 v[110:113], v[168:171], v[180:183], v[110:113]
	v_mfma_f32_16x16x32_bf16 v[98:101], v[160:163], v[202:205], v[98:101]
	v_mfma_f32_16x16x32_bf16 v[94:97], v[168:171], v[202:205], v[94:97]
	v_mfma_f32_16x16x32_bf16 v[82:85], v[160:163], v[210:213], v[82:85]
	v_mfma_f32_16x16x32_bf16 v[78:81], v[168:171], v[210:213], v[78:81]
	v_mfma_f32_16x16x32_bf16 v[70:73], v[160:163], v[218:221], v[70:73]
	v_mfma_f32_16x16x32_bf16 v[66:69], v[168:171], v[218:221], v[66:69]
	s_setprio 0
	s_barrier
	s_add_i32 s38, s38, s0
	v_lshl_add_u64 v[176:177], s[34:35], 0, v[0:1]
	s_mov_b32 m0, s38
	ds_read_b128 v[172:175], v159 offset:16384
	ds_read_b128 v[180:183], v159 offset:17408
	ds_read_b128 v[184:187], v159 offset:18432
	ds_read_b128 v[202:205], v159 offset:19456
	ds_read_b128 v[206:209], v159 offset:20480
	ds_read_b128 v[210:213], v159 offset:21504
	ds_read_b128 v[214:217], v159 offset:22528
	ds_read_b128 v[218:221], v159 offset:23552
	global_load_lds_dwordx4 v[176:177], off
	s_add_i32 m0, s38, 0x2000
	v_lshl_add_u64 v[188:189], s[34:35], 0, v[142:143]
	s_add_u32 s34, s34, s44
	s_addc_u32 s35, s35, 0
	s_add_i32 s31, s31, s0
	global_load_lds_dwordx4 v[188:189], off
	v_lshl_add_u64 v[222:223], s[34:35], 0, v[0:1]
	s_mov_b32 m0, s31
	v_lshl_add_u64 v[224:225], s[34:35], 0, v[142:143]
	global_load_lds_dwordx4 v[222:223], off
	s_add_i32 m0, s31, 0x2000
	v_lshl_add_u64 v[226:227], s[12:13], 0, v[0:1]
	global_load_lds_dwordx4 v[224:225], off
	s_mov_b32 m0, s1
	v_lshl_add_u64 v[228:229], s[12:13], 0, v[142:143]
	global_load_lds_dwordx4 v[226:227], off
	s_mov_b32 m0, s14
	s_nop 0
	global_load_lds_dwordx4 v[228:229], off
	s_waitcnt vmcnt(8)
	s_waitcnt lgkmcnt(0)
	s_barrier
; #define PG8_STAGE(bufoff, gbase, voff) do { _Pragma("unroll") for (int _i = 0; _i < 2; ++_i) \
;         __builtin_amdgcn_global_load_lds((const unsigned*)((const char*)(gbase) + (voff)[_i]), (PG8_LAS unsigned*)(lds + (bufoff) + ldsw + _i * 8192), 16, 0, 0); } while (0)
; #define PG8_LDA(dst, b, h) do { _Pragma("unroll") for (int m = 0; m < 4; ++m) _Pragma("unroll") for (int k = 0; k < 2; ++k) dst[m][k] = *(const PG8_LAS bf16x8*)(lds + PG8_SA(b, h) + aoff + m * 2048 + k * 1024); } while (0)
; #define PG8_LDB(dst, b, h) do { _Pragma("unroll") for (int n = 0; n < 2; ++n) _Pragma("unroll") for (int k = 0; k < 2; ++k) dst[n][k] = *(const PG8_LAS bf16x8*)(lds + PG8_SB(b, h) + boff + n * 2048 + k * 1024); } while (0)
; #define PG8_MMA(ai, bj, At, Bt) do { __builtin_amdgcn_s_setprio(1); _Pragma("unroll") for (int m = 0; m < 4; ++m) _Pragma("unroll") for (int n = 0; n < 2; ++n) _Pragma("unroll") for (int k = 0; k < 2; ++k) \
;         acc[ai][bj][m][n] = __builtin_amdgcn_mfma_f32_16x16x32_bf16(Bt[n][k], At[m][k], acc[ai][bj][m][n], 0, 0, 0); __builtin_amdgcn_s_setprio(0); } while (0)
; #define PG8_WAIT_V(n) asm volatile("s_waitcnt vmcnt(" #n ")" ::: "memory")
; #define PG8_WAIT_L(n) asm volatile("s_waitcnt lgkmcnt(" #n ")" ::: "memory")
; #define PG8_BAR __builtin_amdgcn_s_barrier()
; #define PG8_SCHED __builtin_amdgcn_sched_barrier(0)
; template <class Epi, class Sched, bool ALIGN_EPI = false, bool SP2 = false>
; __device__ __forceinline__ void gemm_phase(PG8_LAS unsigned char* lds, const Gemm g, const Sched& S, const Epi& E) {
;     ...
;             PG8_WAIT_V(8); PG8_WAIT_L(0); PG8_BAR; PG8_MMA(1, 0, At, B0); PG8_MMA(1, 1, At, B1); PG8_BAR; PG8_SCHED;
;             PG8_LDB(B0, 1, 0); PG8_LDB(B1, 1, 1); PG8_SCHED; PG8_LDA(At, 1, 0); PG8_STAGE(PG8_SA(0, 1), a2 + hstep, voffA);
;             PG8_WAIT_V(8); PG8_WAIT_L(0); PG8_BAR; PG8_MMA(0, 0, At, B0); PG8_MMA(0, 1, At, B1); PG8_BAR; PG8_SCHED;
;             PG8_LDA(At, 1, 1); PG8_STAGE(PG8_SB(1, 0), b3, voffB); PG8_STAGE(PG8_SB(1, 1), b3 + hstep, voffB); PG8_STAGE(PG8_SA(1, 0), a3, voffA);
	s_setprio 1
	s_waitcnt lgkmcnt(0)
	v_mfma_f32_16x16x32_bf16 v[62:65], v[130:133], v[172:175], v[62:65]
	v_mfma_f32_16x16x32_bf16 v[58:61], v[138:141], v[172:175], v[58:61]
	v_mfma_f32_16x16x32_bf16 v[54:57], v[130:133], v[184:187], v[54:57]
	v_mfma_f32_16x16x32_bf16 v[42:45], v[138:141], v[184:187], v[42:45]
	v_mfma_f32_16x16x32_bf16 v[38:41], v[130:133], v[206:209], v[38:41]
	v_mfma_f32_16x16x32_bf16 v[26:29], v[138:141], v[206:209], v[26:29]
	v_mfma_f32_16x16x32_bf16 v[22:25], v[130:133], v[214:217], v[22:25]
	v_mfma_f32_16x16x32_bf16 v[10:13], v[138:141], v[214:217], v[10:13]
	v_mfma_f32_16x16x32_bf16 v[62:65], v[134:137], v[180:183], v[62:65]
	v_mfma_f32_16x16x32_bf16 v[58:61], v[148:151], v[180:183], v[58:61]
	v_mfma_f32_16x16x32_bf16 v[54:57], v[134:137], v[202:205], v[54:57]
	v_mfma_f32_16x16x32_bf16 v[42:45], v[148:151], v[202:205], v[42:45]
	v_mfma_f32_16x16x32_bf16 v[38:41], v[134:137], v[210:213], v[38:41]
	v_mfma_f32_16x16x32_bf16 v[26:29], v[148:151], v[210:213], v[26:29]
	v_mfma_f32_16x16x32_bf16 v[22:25], v[134:137], v[218:221], v[22:25]
	v_mfma_f32_16x16x32_bf16 v[10:13], v[148:151], v[218:221], v[10:13]
	v_mfma_f32_16x16x32_bf16 v[50:53], v[152:155], v[172:175], v[50:53]
	v_mfma_f32_16x16x32_bf16 v[46:49], v[164:167], v[172:175], v[46:49]
	v_mfma_f32_16x16x32_bf16 v[34:37], v[152:155], v[184:187], v[34:37]
	v_mfma_f32_16x16x32_bf16 v[30:33], v[164:167], v[184:187], v[30:33]
	v_mfma_f32_16x16x32_bf16 v[18:21], v[152:155], v[206:209], v[18:21]
	v_mfma_f32_16x16x32_bf16 v[14:17], v[164:167], v[206:209], v[14:17]
	v_mfma_f32_16x16x32_bf16 v[6:9], v[152:155], v[214:217], v[6:9]
	v_mfma_f32_16x16x32_bf16 v[2:5], v[164:167], v[214:217], v[2:5]
	v_mfma_f32_16x16x32_bf16 v[50:53], v[160:163], v[180:183], v[50:53]
	v_mfma_f32_16x16x32_bf16 v[46:49], v[168:171], v[180:183], v[46:49]
	v_mfma_f32_16x16x32_bf16 v[34:37], v[160:163], v[202:205], v[34:37]
	v_mfma_f32_16x16x32_bf16 v[30:33], v[168:171], v[202:205], v[30:33]
	v_mfma_f32_16x16x32_bf16 v[18:21], v[160:163], v[210:213], v[18:21]
	v_mfma_f32_16x16x32_bf16 v[14:17], v[168:171], v[210:213], v[14:17]
	v_mfma_f32_16x16x32_bf16 v[6:9], v[160:163], v[218:221], v[6:9]
	v_mfma_f32_16x16x32_bf16 v[2:5], v[168:171], v[218:221], v[2:5]
	s_setprio 0
	s_barrier
	s_add_i32 s31, 0, 0x18000
	s_add_i32 s34, 0, 0x1c000
	v_add_u32_e32 v148, s31, v157
	v_add_u32_e32 v168, s34, v157
	ds_read_b128 v[130:133], v148
	ds_read_b128 v[134:137], v148 offset:1024
	ds_read_b128 v[138:141], v148 offset:2048
	ds_read_b128 v[148:151], v148 offset:3072
	ds_read_b128 v[152:155], v168
	ds_read_b128 v[160:163], v168 offset:1024
	ds_read_b128 v[164:167], v168 offset:2048
	ds_read_b128 v[168:171], v168 offset:3072
	s_add_u32 s12, s12, s44
	s_addc_u32 s13, s13, 0
	s_mov_b32 m0, s16
	v_lshl_add_u64 v[230:231], s[12:13], 0, v[0:1]
	ds_read_b128 v[172:175], v159 offset:32768
	ds_read_b128 v[180:183], v159 offset:33792
	ds_read_b128 v[184:187], v159 offset:34816
	ds_read_b128 v[202:205], v159 offset:35840
	ds_read_b128 v[206:209], v159 offset:36864
	ds_read_b128 v[210:213], v159 offset:37888
	ds_read_b128 v[214:217], v159 offset:38912
	ds_read_b128 v[218:221], v159 offset:39936
	global_load_lds_dwordx4 v[230:231], off
	v_lshl_add_u64 v[230:231], s[12:13], 0, v[142:143]
	s_mov_b32 m0, s17
	s_nop 0
	global_load_lds_dwordx4 v[230:231], off
	s_waitcnt vmcnt(8)
	s_waitcnt lgkmcnt(0)
	s_barrier
	s_setprio 1
	s_waitcnt lgkmcnt(0)
	v_mfma_f32_16x16x32_bf16 v[126:129], v[130:133], v[172:175], v[126:129]
	v_mfma_f32_16x16x32_bf16 v[122:125], v[138:141], v[172:175], v[122:125]
	v_mfma_f32_16x16x32_bf16 v[118:121], v[130:133], v[184:187], v[118:121]
	v_mfma_f32_16x16x32_bf16 v[106:109], v[138:141], v[184:187], v[106:109]
	v_mfma_f32_16x16x32_bf16 v[102:105], v[130:133], v[206:209], v[102:105]
	v_mfma_f32_16x16x32_bf16 v[90:93], v[138:141], v[206:209], v[90:93]
	v_mfma_f32_16x16x32_bf16 v[86:89], v[130:133], v[214:217], v[86:89]
	v_mfma_f32_16x16x32_bf16 v[74:77], v[138:141], v[214:217], v[74:77]
	v_mfma_f32_16x16x32_bf16 v[126:129], v[134:137], v[180:183], v[126:129]
	v_mfma_f32_16x16x32_bf16 v[122:125], v[148:151], v[180:183], v[122:125]
	v_mfma_f32_16x16x32_bf16 v[118:121], v[134:137], v[202:205], v[118:121]
	v_mfma_f32_16x16x32_bf16 v[106:109], v[148:151], v[202:205], v[106:109]
	v_mfma_f32_16x16x32_bf16 v[102:105], v[134:137], v[210:213], v[102:105]
	v_mfma_f32_16x16x32_bf16 v[90:93], v[148:151], v[210:213], v[90:93]
	v_mfma_f32_16x16x32_bf16 v[86:89], v[134:137], v[218:221], v[86:89]
	v_mfma_f32_16x16x32_bf16 v[74:77], v[148:151], v[218:221], v[74:77]
	v_mfma_f32_16x16x32_bf16 v[114:117], v[152:155], v[172:175], v[114:117]
	v_mfma_f32_16x16x32_bf16 v[110:113], v[164:167], v[172:175], v[110:113]
	v_mfma_f32_16x16x32_bf16 v[98:101], v[152:155], v[184:187], v[98:101]
	v_mfma_f32_16x16x32_bf16 v[94:97], v[164:167], v[184:187], v[94:97]
	v_mfma_f32_16x16x32_bf16 v[82:85], v[152:155], v[206:209], v[82:85]
	v_mfma_f32_16x16x32_bf16 v[78:81], v[164:167], v[206:209], v[78:81]
	v_mfma_f32_16x16x32_bf16 v[70:73], v[152:155], v[214:217], v[70:73]
	v_mfma_f32_16x16x32_bf16 v[66:69], v[164:167], v[214:217], v[66:69]
	v_mfma_f32_16x16x32_bf16 v[114:117], v[160:163], v[180:183], v[114:117]
	v_mfma_f32_16x16x32_bf16 v[110:113], v[168:171], v[180:183], v[110:113]
	v_mfma_f32_16x16x32_bf16 v[98:101], v[160:163], v[202:205], v[98:101]
	v_mfma_f32_16x16x32_bf16 v[94:97], v[168:171], v[202:205], v[94:97]
	v_mfma_f32_16x16x32_bf16 v[82:85], v[160:163], v[210:213], v[82:85]
	v_mfma_f32_16x16x32_bf16 v[78:81], v[168:171], v[210:213], v[78:81]
	v_mfma_f32_16x16x32_bf16 v[70:73], v[160:163], v[218:221], v[70:73]
	v_mfma_f32_16x16x32_bf16 v[66:69], v[168:171], v[218:221], v[66:69]
	s_setprio 0
	s_barrier
; #define PG8_STAGE(bufoff, gbase, voff) do { _Pragma("unroll") for (int _i = 0; _i < 2; ++_i) \
;         __builtin_amdgcn_global_load_lds((const unsigned*)((const char*)(gbase) + (voff)[_i]), (PG8_LAS unsigned*)(lds + (bufoff) + ldsw + _i * 8192), 16, 0, 0); } while (0)
; #define PG8_LDA(dst, b, h) do { _Pragma("unroll") for (int m = 0; m < 4; ++m) _Pragma("unroll") for (int k = 0; k < 2; ++k) dst[m][k] = *(const PG8_LAS bf16x8*)(lds + PG8_SA(b, h) + aoff + m * 2048 + k * 1024); } while (0)
; #define PG8_MMA(ai, bj, At, Bt) do { __builtin_amdgcn_s_setprio(1); _Pragma("unroll") for (int m = 0; m < 4; ++m) _Pragma("unroll") for (int n = 0; n < 2; ++n) _Pragma("unroll") for (int k = 0; k < 2; ++k) \
;         acc[ai][bj][m][n] = __builtin_amdgcn_mfma_f32_16x16x32_bf16(Bt[n][k], At[m][k], acc[ai][bj][m][n], 0, 0, 0); __builtin_amdgcn_s_setprio(0); } while (0)
; #define PG8_WAIT_V(n) asm volatile("s_waitcnt vmcnt(" #n ")" ::: "memory")
; #define PG8_WAIT_L(n) asm volatile("s_waitcnt lgkmcnt(" #n ")" ::: "memory")
; #define PG8_BAR __builtin_amdgcn_s_barrier()
; #define PG8_SCHED __builtin_amdgcn_sched_barrier(0)
; template <class Epi, class Sched, bool ALIGN_EPI = false, bool SP2 = false>
; __device__ __forceinline__ void gemm_phase(PG8_LAS unsigned char* lds, const Gemm g, const Sched& S, const Epi& E) {
;     ...
;             PG8_WAIT_V(8); PG8_WAIT_L(0); PG8_BAR; PG8_MMA(0, 0, At, B0); PG8_MMA(0, 1, At, B1); PG8_BAR; PG8_SCHED;
;             PG8_LDA(At, 1, 1); PG8_STAGE(PG8_SB(1, 0), b3, voffB); PG8_STAGE(PG8_SB(1, 1), b3 + hstep, voffB); PG8_STAGE(PG8_SA(1, 0), a3, voffA);
;             PG8_WAIT_V(8); PG8_WAIT_L(0); PG8_BAR; PG8_MMA(1, 0, At, B0); PG8_MMA(1, 1, At, B1); PG8_BAR; PG8_SCHED;
;     ...
;         if constexpr (ALIGN_EPI) { if (wr == 0) PG8_BAR; }
	s_add_i32 s12, s31, s0
	v_lshl_add_u64 v[176:177], v[176:177], 0, s[36:37]
	s_mov_b32 m0, s12
	ds_read_b128 v[172:175], v159 offset:49152
	ds_read_b128 v[180:183], v159 offset:50176
	ds_read_b128 v[184:187], v159 offset:51200
	ds_read_b128 v[202:205], v159 offset:52224
	ds_read_b128 v[206:209], v159 offset:53248
	ds_read_b128 v[210:213], v159 offset:54272
	ds_read_b128 v[214:217], v159 offset:55296
	ds_read_b128 v[218:221], v159 offset:56320
	global_load_lds_dwordx4 v[176:177], off
	v_lshl_add_u64 v[176:177], v[188:189], 0, s[36:37]
	s_add_i32 m0, s12, 0x2000
	s_add_i32 s12, s34, s0
	global_load_lds_dwordx4 v[176:177], off
	v_lshl_add_u64 v[176:177], v[222:223], 0, s[36:37]
	s_mov_b32 m0, s12
	s_nop 0
	global_load_lds_dwordx4 v[176:177], off
	v_lshl_add_u64 v[176:177], v[224:225], 0, s[36:37]
	s_add_i32 m0, s12, 0x2000
	s_nop 0
	global_load_lds_dwordx4 v[176:177], off
	v_lshl_add_u64 v[176:177], v[226:227], 0, s[36:37]
	s_mov_b32 m0, s18
	s_nop 0
	global_load_lds_dwordx4 v[176:177], off
	v_lshl_add_u64 v[176:177], v[228:229], 0, s[36:37]
	s_mov_b32 m0, s19
	s_nop 0
	global_load_lds_dwordx4 v[176:177], off
	s_waitcnt vmcnt(8)
	s_waitcnt lgkmcnt(0)
	s_barrier
	s_setprio 1
	s_waitcnt lgkmcnt(0)
	v_mfma_f32_16x16x32_bf16 v[62:65], v[130:133], v[172:175], v[62:65]
	v_mfma_f32_16x16x32_bf16 v[58:61], v[138:141], v[172:175], v[58:61]
	v_mfma_f32_16x16x32_bf16 v[54:57], v[130:133], v[184:187], v[54:57]
	v_mfma_f32_16x16x32_bf16 v[42:45], v[138:141], v[184:187], v[42:45]
	v_mfma_f32_16x16x32_bf16 v[38:41], v[130:133], v[206:209], v[38:41]
	v_mfma_f32_16x16x32_bf16 v[26:29], v[138:141], v[206:209], v[26:29]
	v_mfma_f32_16x16x32_bf16 v[22:25], v[130:133], v[214:217], v[22:25]
	v_mfma_f32_16x16x32_bf16 v[10:13], v[138:141], v[214:217], v[10:13]
	v_mfma_f32_16x16x32_bf16 v[62:65], v[134:137], v[180:183], v[62:65]
	v_mfma_f32_16x16x32_bf16 v[58:61], v[148:151], v[180:183], v[58:61]
	v_mfma_f32_16x16x32_bf16 v[54:57], v[134:137], v[202:205], v[54:57]
	v_mfma_f32_16x16x32_bf16 v[42:45], v[148:151], v[202:205], v[42:45]
	v_mfma_f32_16x16x32_bf16 v[38:41], v[134:137], v[210:213], v[38:41]
	v_mfma_f32_16x16x32_bf16 v[26:29], v[148:151], v[210:213], v[26:29]
	v_mfma_f32_16x16x32_bf16 v[22:25], v[134:137], v[218:221], v[22:25]
	v_mfma_f32_16x16x32_bf16 v[10:13], v[148:151], v[218:221], v[10:13]
	v_mfma_f32_16x16x32_bf16 v[50:53], v[152:155], v[172:175], v[50:53]
	v_mfma_f32_16x16x32_bf16 v[46:49], v[164:167], v[172:175], v[46:49]
	v_mfma_f32_16x16x32_bf16 v[34:37], v[152:155], v[184:187], v[34:37]
	v_mfma_f32_16x16x32_bf16 v[30:33], v[164:167], v[184:187], v[30:33]
	v_mfma_f32_16x16x32_bf16 v[18:21], v[152:155], v[206:209], v[18:21]
	v_mfma_f32_16x16x32_bf16 v[14:17], v[164:167], v[206:209], v[14:17]
	v_mfma_f32_16x16x32_bf16 v[6:9], v[152:155], v[214:217], v[6:9]
	v_mfma_f32_16x16x32_bf16 v[2:5], v[164:167], v[214:217], v[2:5]
	v_mfma_f32_16x16x32_bf16 v[50:53], v[160:163], v[180:183], v[50:53]
	v_mfma_f32_16x16x32_bf16 v[46:49], v[168:171], v[180:183], v[46:49]
	v_mfma_f32_16x16x32_bf16 v[34:37], v[160:163], v[202:205], v[34:37]
	v_mfma_f32_16x16x32_bf16 v[30:33], v[168:171], v[202:205], v[30:33]
	v_mfma_f32_16x16x32_bf16 v[18:21], v[160:163], v[210:213], v[18:21]
	v_mfma_f32_16x16x32_bf16 v[14:17], v[168:171], v[210:213], v[14:17]
	v_mfma_f32_16x16x32_bf16 v[6:9], v[160:163], v[218:221], v[6:9]
	v_mfma_f32_16x16x32_bf16 v[2:5], v[168:171], v[218:221], v[2:5]
	s_setprio 0
	s_barrier
	s_add_u32 s10, s10, 0x100
	s_addc_u32 s11, s11, 0
	s_add_u32 s28, s28, 0x100
	s_addc_u32 s29, s29, 0
	s_cmp_ge_u32 s30, s40
	s_mov_b32 s12, s30
	s_cbranch_scc0 .LBB0_179
	s_and_b64 vcc, exec, s[4:5]
	s_cbranch_vccz .LBB0_182
	s_barrier

; #define PG8_STAGE(bufoff, gbase, voff) do { _Pragma("unroll") for (int _i = 0; _i < 2; ++_i) \
;         __builtin_amdgcn_global_load_lds((const unsigned*)((const char*)(gbase) + (voff)[_i]), (PG8_LAS unsigned*)(lds + (bufoff) + ldsw + _i * 8192), 16, 0, 0); } while (0)
; #define PG8_LDA(dst, b, h) do { _Pragma("unroll") for (int m = 0; m < 4; ++m) _Pragma("unroll") for (int k = 0; k < 2; ++k) dst[m][k] = *(const PG8_LAS bf16x8*)(lds + PG8_SA(b, h) + aoff + m * 2048 + k * 1024); } while (0)
; #define PG8_LDB(dst, b, h) do { _Pragma("unroll") for (int n = 0; n < 2; ++n) _Pragma("unroll") for (int k = 0; k < 2; ++k) dst[n][k] = *(const PG8_LAS bf16x8*)(lds + PG8_SB(b, h) + boff + n * 2048 + k * 1024); } while (0)
; #define PG8_MMA(ai, bj, At, Bt) do { __builtin_amdgcn_s_setprio(1); _Pragma("unroll") for (int m = 0; m < 4; ++m) _Pragma("unroll") for (int n = 0; n < 2; ++n) _Pragma("unroll") for (int k = 0; k < 2; ++k) \
;         acc[ai][bj][m][n] = __builtin_amdgcn_mfma_f32_16x16x32_bf16(Bt[n][k], At[m][k], acc[ai][bj][m][n], 0, 0, 0); __builtin_amdgcn_s_setprio(0); } while (0)
; #define PG8_WAIT_V(n) asm volatile("s_waitcnt vmcnt(" #n ")" ::: "memory")
; #define PG8_WAIT_L(n) asm volatile("s_waitcnt lgkmcnt(" #n ")" ::: "memory")
; #define PG8_BAR __builtin_amdgcn_s_barrier()
; #define PG8_SCHED __builtin_amdgcn_sched_barrier(0)
; template <class Epi, class Sched, bool ALIGN_EPI = false, bool SP2 = false>
; __device__ __forceinline__ void gemm_phase(PG8_LAS unsigned char* lds, const Gemm g, const Sched& S, const Epi& E) {
;     ...
;             PG8_LDB(B0, 0, 0); PG8_LDB(B1, 0, 1); PG8_SCHED; PG8_LDA(At, 0, 0); PG8_STAGE(PG8_SA(1, 1), a1 + hstep, voffA);
;             PG8_WAIT_V(8); PG8_WAIT_L(0); PG8_BAR; PG8_MMA(0, 0, At, B0); PG8_MMA(0, 1, At, B1); PG8_BAR; PG8_SCHED;
;             PG8_LDA(At, 0, 1); PG8_STAGE(PG8_SB(0, 0), b2, voffB); PG8_STAGE(PG8_SB(0, 1), b2 + hstep, voffB); PG8_STAGE(PG8_SA(0, 0), a2, voffA);
;             PG8_WAIT_V(8); PG8_WAIT_L(0); PG8_BAR; PG8_MMA(1, 0, At, B0); PG8_MMA(1, 1, At, B1); PG8_BAR; PG8_SCHED;
.LBB0_496:
	s_add_u32 s16, s20, 0xfff80080
	s_addc_u32 s17, s21, -1
	s_add_i32 s41, 0, 0x10000
	s_cmp_eq_u32 s40, 28
	s_cselect_b32 s19, s9, s17
	s_cselect_b32 s18, s34, s16
	s_cselect_b32 s17, s7, s39
	s_cselect_b32 s16, s35, s38
	s_add_i32 s46, 0, 0x14000
	v_add_u32_e32 v156, s41, v145
	v_add_u32_e32 v172, s46, v145
	ds_read_b128 v[140:143], v156
	ds_read_b128 v[148:151], v156 offset:1024
	ds_read_b128 v[152:155], v156 offset:2048
	ds_read_b128 v[156:159], v156 offset:3072
	ds_read_b128 v[160:163], v172
	ds_read_b128 v[164:167], v172 offset:1024
	ds_read_b128 v[168:171], v172 offset:2048
	ds_read_b128 v[172:175], v172 offset:3072
	v_lshl_add_u64 v[176:177], s[20:21], 0, v[136:137]
	s_add_i32 m0, s1, 0xc000
	ds_read_b128 v[184:187], v147
	ds_read_b128 v[202:205], v147 offset:1024
	ds_read_b128 v[206:209], v147 offset:2048
	ds_read_b128 v[210:213], v147 offset:3072
	ds_read_b128 v[214:217], v147 offset:4096
	ds_read_b128 v[218:221], v147 offset:5120
	ds_read_b128 v[222:225], v147 offset:6144
	ds_read_b128 v[226:229], v147 offset:7168
	global_load_lds_dwordx4 v[176:177], off
	v_lshl_add_u64 v[176:177], s[20:21], 0, v[138:139]
	s_add_i32 m0, s1, 0xe000
	s_nop 0
	global_load_lds_dwordx4 v[176:177], off
	s_waitcnt vmcnt(8)
	s_waitcnt lgkmcnt(0)
	s_barrier
	s_setprio 1
	s_waitcnt lgkmcnt(0)
	v_mfma_f32_16x16x32_bf16 v[126:129], v[140:143], v[184:187], v[126:129]
	v_mfma_f32_16x16x32_bf16 v[122:125], v[152:155], v[184:187], v[122:125]
	v_mfma_f32_16x16x32_bf16 v[118:121], v[140:143], v[206:209], v[118:121]
	v_mfma_f32_16x16x32_bf16 v[110:113], v[152:155], v[206:209], v[110:113]
	v_mfma_f32_16x16x32_bf16 v[102:105], v[140:143], v[214:217], v[102:105]
	v_mfma_f32_16x16x32_bf16 v[94:97], v[152:155], v[214:217], v[94:97]
	v_mfma_f32_16x16x32_bf16 v[86:89], v[140:143], v[222:225], v[86:89]
	v_mfma_f32_16x16x32_bf16 v[78:81], v[152:155], v[222:225], v[78:81]
	v_mfma_f32_16x16x32_bf16 v[126:129], v[148:151], v[202:205], v[126:129]
	v_mfma_f32_16x16x32_bf16 v[122:125], v[156:159], v[202:205], v[122:125]
	v_mfma_f32_16x16x32_bf16 v[118:121], v[148:151], v[210:213], v[118:121]
	v_mfma_f32_16x16x32_bf16 v[110:113], v[156:159], v[210:213], v[110:113]
	v_mfma_f32_16x16x32_bf16 v[102:105], v[148:151], v[218:221], v[102:105]
	v_mfma_f32_16x16x32_bf16 v[94:97], v[156:159], v[218:221], v[94:97]
	v_mfma_f32_16x16x32_bf16 v[86:89], v[148:151], v[226:229], v[86:89]
	v_mfma_f32_16x16x32_bf16 v[78:81], v[156:159], v[226:229], v[78:81]
	v_mfma_f32_16x16x32_bf16 v[114:117], v[160:163], v[184:187], v[114:117]
	v_mfma_f32_16x16x32_bf16 v[106:109], v[168:171], v[184:187], v[106:109]
	v_mfma_f32_16x16x32_bf16 v[98:101], v[160:163], v[206:209], v[98:101]
	v_mfma_f32_16x16x32_bf16 v[90:93], v[168:171], v[206:209], v[90:93]
	v_mfma_f32_16x16x32_bf16 v[82:85], v[160:163], v[214:217], v[82:85]
	v_mfma_f32_16x16x32_bf16 v[74:77], v[168:171], v[214:217], v[74:77]
	v_mfma_f32_16x16x32_bf16 v[70:73], v[160:163], v[222:225], v[70:73]
	v_mfma_f32_16x16x32_bf16 v[66:69], v[168:171], v[222:225], v[66:69]
	v_mfma_f32_16x16x32_bf16 v[114:117], v[164:167], v[202:205], v[114:117]
	v_mfma_f32_16x16x32_bf16 v[106:109], v[172:175], v[202:205], v[106:109]
	v_mfma_f32_16x16x32_bf16 v[98:101], v[164:167], v[210:213], v[98:101]
	v_mfma_f32_16x16x32_bf16 v[90:93], v[172:175], v[210:213], v[90:93]
	v_mfma_f32_16x16x32_bf16 v[82:85], v[164:167], v[218:221], v[82:85]
	v_mfma_f32_16x16x32_bf16 v[74:77], v[172:175], v[218:221], v[74:77]
	v_mfma_f32_16x16x32_bf16 v[70:73], v[164:167], v[226:229], v[70:73]
	v_mfma_f32_16x16x32_bf16 v[66:69], v[172:175], v[226:229], v[66:69]
	s_setprio 0
	s_barrier
	s_add_i32 s41, s41, s0
	v_lshl_add_u64 v[176:177], s[16:17], 0, v[0:1]
	s_mov_b32 m0, s41
	ds_read_b128 v[184:187], v147 offset:16384
	ds_read_b128 v[202:205], v147 offset:17408
	ds_read_b128 v[206:209], v147 offset:18432
	ds_read_b128 v[210:213], v147 offset:19456
	ds_read_b128 v[214:217], v147 offset:20480
	ds_read_b128 v[218:221], v147 offset:21504
	ds_read_b128 v[222:225], v147 offset:22528
	ds_read_b128 v[226:229], v147 offset:23552
	global_load_lds_dwordx4 v[176:177], off
	s_add_i32 m0, s41, 0x2000
	s_add_u32 s44, s16, 0x80000
	v_lshl_add_u64 v[180:181], s[16:17], 0, v[130:131]
	s_addc_u32 s45, s17, 0
	s_add_i32 s41, s46, s0
	global_load_lds_dwordx4 v[180:181], off
	v_lshl_add_u64 v[182:183], s[44:45], 0, v[0:1]
	s_mov_b32 m0, s41
	v_lshl_add_u64 v[188:189], s[18:19], 0, v[132:133]
	global_load_lds_dwordx4 v[182:183], off
	v_lshl_add_u64 v[182:183], s[44:45], 0, v[130:131]
	s_add_i32 m0, s41, 0x2000
	s_nop 0
	global_load_lds_dwordx4 v[182:183], off
	v_lshl_add_u64 v[182:183], s[18:19], 0, v[134:135]
	s_mov_b32 m0, s1
	s_nop 0
	global_load_lds_dwordx4 v[182:183], off
	s_mov_b32 m0, s14
	s_nop 0
	global_load_lds_dwordx4 v[188:189], off
	s_waitcnt vmcnt(8)
	s_waitcnt lgkmcnt(0)
	s_barrier
; #define PG8_STAGE(bufoff, gbase, voff) do { _Pragma("unroll") for (int _i = 0; _i < 2; ++_i) \
;         __builtin_amdgcn_global_load_lds((const unsigned*)((const char*)(gbase) + (voff)[_i]), (PG8_LAS unsigned*)(lds + (bufoff) + ldsw + _i * 8192), 16, 0, 0); } while (0)
; #define PG8_LDA(dst, b, h) do { _Pragma("unroll") for (int m = 0; m < 4; ++m) _Pragma("unroll") for (int k = 0; k < 2; ++k) dst[m][k] = *(const PG8_LAS bf16x8*)(lds + PG8_SA(b, h) + aoff + m * 2048 + k * 1024); } while (0)
; #define PG8_LDB(dst, b, h) do { _Pragma("unroll") for (int n = 0; n < 2; ++n) _Pragma("unroll") for (int k = 0; k < 2; ++k) dst[n][k] = *(const PG8_LAS bf16x8*)(lds + PG8_SB(b, h) + boff + n * 2048 + k * 1024); } while (0)
; #define PG8_MMA(ai, bj, At, Bt) do { __builtin_amdgcn_s_setprio(1); _Pragma("unroll") for (int m = 0; m < 4; ++m) _Pragma("unroll") for (int n = 0; n < 2; ++n) _Pragma("unroll") for (int k = 0; k < 2; ++k) \
;         acc[ai][bj][m][n] = __builtin_amdgcn_mfma_f32_16x16x32_bf16(Bt[n][k], At[m][k], acc[ai][bj][m][n], 0, 0, 0); __builtin_amdgcn_s_setprio(0); } while (0)
; #define PG8_WAIT_V(n) asm volatile("s_waitcnt vmcnt(" #n ")" ::: "memory")
; #define PG8_WAIT_L(n) asm volatile("s_waitcnt lgkmcnt(" #n ")" ::: "memory")
; #define PG8_BAR __builtin_amdgcn_s_barrier()
; #define PG8_SCHED __builtin_amdgcn_sched_barrier(0)
; template <class Epi, class Sched, bool ALIGN_EPI = false, bool SP2 = false>
; __device__ __forceinline__ void gemm_phase(PG8_LAS unsigned char* lds, const Gemm g, const Sched& S, const Epi& E) {
;     ...
;             PG8_WAIT_V(8); PG8_WAIT_L(0); PG8_BAR; PG8_MMA(1, 0, At, B0); PG8_MMA(1, 1, At, B1); PG8_BAR; PG8_SCHED;
;             PG8_LDB(B0, 1, 0); PG8_LDB(B1, 1, 1); PG8_SCHED; PG8_LDA(At, 1, 0); PG8_STAGE(PG8_SA(0, 1), a2 + hstep, voffA);
;             PG8_WAIT_V(8); PG8_WAIT_L(0); PG8_BAR; PG8_MMA(0, 0, At, B0); PG8_MMA(0, 1, At, B1); PG8_BAR; PG8_SCHED;
;             PG8_LDA(At, 1, 1); PG8_STAGE(PG8_SB(1, 0), b3, voffB); PG8_STAGE(PG8_SB(1, 1), b3 + hstep, voffB); PG8_STAGE(PG8_SA(1, 0), a3, voffA);
	s_setprio 1
	s_waitcnt lgkmcnt(0)
	v_mfma_f32_16x16x32_bf16 v[62:65], v[140:143], v[184:187], v[62:65]
	v_mfma_f32_16x16x32_bf16 v[58:61], v[152:155], v[184:187], v[58:61]
	v_mfma_f32_16x16x32_bf16 v[54:57], v[140:143], v[206:209], v[54:57]
	v_mfma_f32_16x16x32_bf16 v[46:49], v[152:155], v[206:209], v[46:49]
	v_mfma_f32_16x16x32_bf16 v[38:41], v[140:143], v[214:217], v[38:41]
	v_mfma_f32_16x16x32_bf16 v[30:33], v[152:155], v[214:217], v[30:33]
	v_mfma_f32_16x16x32_bf16 v[22:25], v[140:143], v[222:225], v[22:25]
	v_mfma_f32_16x16x32_bf16 v[14:17], v[152:155], v[222:225], v[14:17]
	v_mfma_f32_16x16x32_bf16 v[62:65], v[148:151], v[202:205], v[62:65]
	v_mfma_f32_16x16x32_bf16 v[58:61], v[156:159], v[202:205], v[58:61]
	v_mfma_f32_16x16x32_bf16 v[54:57], v[148:151], v[210:213], v[54:57]
	v_mfma_f32_16x16x32_bf16 v[46:49], v[156:159], v[210:213], v[46:49]
	v_mfma_f32_16x16x32_bf16 v[38:41], v[148:151], v[218:221], v[38:41]
	v_mfma_f32_16x16x32_bf16 v[30:33], v[156:159], v[218:221], v[30:33]
	v_mfma_f32_16x16x32_bf16 v[22:25], v[148:151], v[226:229], v[22:25]
	v_mfma_f32_16x16x32_bf16 v[14:17], v[156:159], v[226:229], v[14:17]
	v_mfma_f32_16x16x32_bf16 v[50:53], v[160:163], v[184:187], v[50:53]
	v_mfma_f32_16x16x32_bf16 v[42:45], v[168:171], v[184:187], v[42:45]
	v_mfma_f32_16x16x32_bf16 v[34:37], v[160:163], v[206:209], v[34:37]
	v_mfma_f32_16x16x32_bf16 v[26:29], v[168:171], v[206:209], v[26:29]
	v_mfma_f32_16x16x32_bf16 v[18:21], v[160:163], v[214:217], v[18:21]
	v_mfma_f32_16x16x32_bf16 v[10:13], v[168:171], v[214:217], v[10:13]
	v_mfma_f32_16x16x32_bf16 v[6:9], v[160:163], v[222:225], v[6:9]
	v_mfma_f32_16x16x32_bf16 v[2:5], v[168:171], v[222:225], v[2:5]
	v_mfma_f32_16x16x32_bf16 v[50:53], v[164:167], v[202:205], v[50:53]
	v_mfma_f32_16x16x32_bf16 v[42:45], v[172:175], v[202:205], v[42:45]
	v_mfma_f32_16x16x32_bf16 v[34:37], v[164:167], v[210:213], v[34:37]
	v_mfma_f32_16x16x32_bf16 v[26:29], v[172:175], v[210:213], v[26:29]
	v_mfma_f32_16x16x32_bf16 v[18:21], v[164:167], v[218:221], v[18:21]
	v_mfma_f32_16x16x32_bf16 v[10:13], v[172:175], v[218:221], v[10:13]
	v_mfma_f32_16x16x32_bf16 v[6:9], v[164:167], v[226:229], v[6:9]
	v_mfma_f32_16x16x32_bf16 v[2:5], v[172:175], v[226:229], v[2:5]
	s_setprio 0
	s_barrier
	s_add_i32 s41, 0, 0x18000
	s_add_i32 s44, 0, 0x1c000
	v_add_u32_e32 v156, s41, v145
	v_add_u32_e32 v172, s44, v145
	ds_read_b128 v[140:143], v156
	ds_read_b128 v[148:151], v156 offset:1024
	ds_read_b128 v[152:155], v156 offset:2048
	ds_read_b128 v[156:159], v156 offset:3072
	ds_read_b128 v[160:163], v172
	ds_read_b128 v[164:167], v172 offset:1024
	ds_read_b128 v[168:171], v172 offset:2048
	ds_read_b128 v[172:175], v172 offset:3072
	s_add_u32 s18, s18, 0x80000
	s_addc_u32 s19, s19, 0
	s_mov_b32 m0, s22
	v_lshl_add_u64 v[230:231], s[18:19], 0, v[134:135]
	ds_read_b128 v[184:187], v147 offset:32768
	ds_read_b128 v[202:205], v147 offset:33792
	ds_read_b128 v[206:209], v147 offset:34816
	ds_read_b128 v[210:213], v147 offset:35840
	ds_read_b128 v[214:217], v147 offset:36864
	ds_read_b128 v[218:221], v147 offset:37888
	ds_read_b128 v[222:225], v147 offset:38912
	ds_read_b128 v[226:229], v147 offset:39936
	global_load_lds_dwordx4 v[230:231], off
	v_lshl_add_u64 v[230:231], s[18:19], 0, v[132:133]
	s_mov_b32 m0, s24
	s_nop 0
	global_load_lds_dwordx4 v[230:231], off
	s_waitcnt vmcnt(8)
	s_waitcnt lgkmcnt(0)
	s_barrier
	s_setprio 1
	s_waitcnt lgkmcnt(0)
	v_mfma_f32_16x16x32_bf16 v[126:129], v[140:143], v[184:187], v[126:129]
	v_mfma_f32_16x16x32_bf16 v[122:125], v[152:155], v[184:187], v[122:125]
	v_mfma_f32_16x16x32_bf16 v[118:121], v[140:143], v[206:209], v[118:121]
	v_mfma_f32_16x16x32_bf16 v[110:113], v[152:155], v[206:209], v[110:113]
	v_mfma_f32_16x16x32_bf16 v[102:105], v[140:143], v[214:217], v[102:105]
	v_mfma_f32_16x16x32_bf16 v[94:97], v[152:155], v[214:217], v[94:97]
	v_mfma_f32_16x16x32_bf16 v[86:89], v[140:143], v[222:225], v[86:89]
	v_mfma_f32_16x16x32_bf16 v[78:81], v[152:155], v[222:225], v[78:81]
	v_mfma_f32_16x16x32_bf16 v[126:129], v[148:151], v[202:205], v[126:129]
	v_mfma_f32_16x16x32_bf16 v[122:125], v[156:159], v[202:205], v[122:125]
	v_mfma_f32_16x16x32_bf16 v[118:121], v[148:151], v[210:213], v[118:121]
	v_mfma_f32_16x16x32_bf16 v[110:113], v[156:159], v[210:213], v[110:113]
	v_mfma_f32_16x16x32_bf16 v[102:105], v[148:151], v[218:221], v[102:105]
	v_mfma_f32_16x16x32_bf16 v[94:97], v[156:159], v[218:221], v[94:97]
	v_mfma_f32_16x16x32_bf16 v[86:89], v[148:151], v[226:229], v[86:89]
	v_mfma_f32_16x16x32_bf16 v[78:81], v[156:159], v[226:229], v[78:81]
	v_mfma_f32_16x16x32_bf16 v[114:117], v[160:163], v[184:187], v[114:117]
	v_mfma_f32_16x16x32_bf16 v[106:109], v[168:171], v[184:187], v[106:109]
	v_mfma_f32_16x16x32_bf16 v[98:101], v[160:163], v[206:209], v[98:101]
	v_mfma_f32_16x16x32_bf16 v[90:93], v[168:171], v[206:209], v[90:93]
	v_mfma_f32_16x16x32_bf16 v[82:85], v[160:163], v[214:217], v[82:85]
	v_mfma_f32_16x16x32_bf16 v[74:77], v[168:171], v[214:217], v[74:77]
	v_mfma_f32_16x16x32_bf16 v[70:73], v[160:163], v[222:225], v[70:73]
	v_mfma_f32_16x16x32_bf16 v[66:69], v[168:171], v[222:225], v[66:69]
	v_mfma_f32_16x16x32_bf16 v[114:117], v[164:167], v[202:205], v[114:117]
	v_mfma_f32_16x16x32_bf16 v[106:109], v[172:175], v[202:205], v[106:109]
	v_mfma_f32_16x16x32_bf16 v[98:101], v[164:167], v[210:213], v[98:101]
	v_mfma_f32_16x16x32_bf16 v[90:93], v[172:175], v[210:213], v[90:93]
	v_mfma_f32_16x16x32_bf16 v[82:85], v[164:167], v[218:221], v[82:85]
	v_mfma_f32_16x16x32_bf16 v[74:77], v[172:175], v[218:221], v[74:77]
	v_mfma_f32_16x16x32_bf16 v[70:73], v[164:167], v[226:229], v[70:73]
	v_mfma_f32_16x16x32_bf16 v[66:69], v[172:175], v[226:229], v[66:69]
	s_setprio 0
	s_barrier
; #define PG8_STAGE(bufoff, gbase, voff) do { _Pragma("unroll") for (int _i = 0; _i < 2; ++_i) \
;         __builtin_amdgcn_global_load_lds((const unsigned*)((const char*)(gbase) + (voff)[_i]), (PG8_LAS unsigned*)(lds + (bufoff) + ldsw + _i * 8192), 16, 0, 0); } while (0)
; #define PG8_LDA(dst, b, h) do { _Pragma("unroll") for (int m = 0; m < 4; ++m) _Pragma("unroll") for (int k = 0; k < 2; ++k) dst[m][k] = *(const PG8_LAS bf16x8*)(lds + PG8_SA(b, h) + aoff + m * 2048 + k * 1024); } while (0)
; #define PG8_MMA(ai, bj, At, Bt) do { __builtin_amdgcn_s_setprio(1); _Pragma("unroll") for (int m = 0; m < 4; ++m) _Pragma("unroll") for (int n = 0; n < 2; ++n) _Pragma("unroll") for (int k = 0; k < 2; ++k) \
;         acc[ai][bj][m][n] = __builtin_amdgcn_mfma_f32_16x16x32_bf16(Bt[n][k], At[m][k], acc[ai][bj][m][n], 0, 0, 0); __builtin_amdgcn_s_setprio(0); } while (0)
; #define PG8_WAIT_V(n) asm volatile("s_waitcnt vmcnt(" #n ")" ::: "memory")
; #define PG8_WAIT_L(n) asm volatile("s_waitcnt lgkmcnt(" #n ")" ::: "memory")
; #define PG8_BAR __builtin_amdgcn_s_barrier()
; #define PG8_SCHED __builtin_amdgcn_sched_barrier(0)
; template <class Epi, class Sched, bool ALIGN_EPI = false, bool SP2 = false>
; __device__ __forceinline__ void gemm_phase(PG8_LAS unsigned char* lds, const Gemm g, const Sched& S, const Epi& E) {
;     ...
;             PG8_WAIT_V(8); PG8_WAIT_L(0); PG8_BAR; PG8_MMA(0, 0, At, B0); PG8_MMA(0, 1, At, B1); PG8_BAR; PG8_SCHED;
;             PG8_LDA(At, 1, 1); PG8_STAGE(PG8_SB(1, 0), b3, voffB); PG8_STAGE(PG8_SB(1, 1), b3 + hstep, voffB); PG8_STAGE(PG8_SA(1, 0), a3, voffA);
;             PG8_WAIT_V(8); PG8_WAIT_L(0); PG8_BAR; PG8_MMA(1, 0, At, B0); PG8_MMA(1, 1, At, B1); PG8_BAR; PG8_SCHED;
;     ...
;         if constexpr (ALIGN_EPI) { if (wr == 0) PG8_BAR; }
	s_add_i32 s18, s41, s0
	v_lshl_add_u64 v[176:177], v[176:177], 0, s[36:37]
	s_mov_b32 m0, s18
	ds_read_b128 v[184:187], v147 offset:49152
	ds_read_b128 v[202:205], v147 offset:50176
	ds_read_b128 v[206:209], v147 offset:51200
	ds_read_b128 v[210:213], v147 offset:52224
	ds_read_b128 v[214:217], v147 offset:53248
	ds_read_b128 v[218:221], v147 offset:54272
	ds_read_b128 v[222:225], v147 offset:55296
	ds_read_b128 v[226:229], v147 offset:56320
	global_load_lds_dwordx4 v[176:177], off
	s_add_i32 m0, s18, 0x2000
	s_add_u32 s16, s16, 0x80080
	v_lshl_add_u64 v[176:177], v[180:181], 0, s[36:37]
	s_addc_u32 s17, s17, 0
	s_add_i32 s18, s44, s0
	global_load_lds_dwordx4 v[176:177], off
	v_lshl_add_u64 v[176:177], s[16:17], 0, v[0:1]
	s_mov_b32 m0, s18
	s_nop 0
	global_load_lds_dwordx4 v[176:177], off
	v_lshl_add_u64 v[176:177], s[16:17], 0, v[130:131]
	s_add_i32 m0, s18, 0x2000
	s_nop 0
	global_load_lds_dwordx4 v[176:177], off
	v_lshl_add_u64 v[176:177], v[182:183], 0, s[36:37]
	s_mov_b32 m0, s25
	s_nop 0
	global_load_lds_dwordx4 v[176:177], off
	v_lshl_add_u64 v[176:177], v[188:189], 0, s[36:37]
	s_mov_b32 m0, s28
	s_nop 0
	global_load_lds_dwordx4 v[176:177], off
	s_waitcnt vmcnt(8)
	s_waitcnt lgkmcnt(0)
	s_barrier
	s_setprio 1
	s_waitcnt lgkmcnt(0)
	v_mfma_f32_16x16x32_bf16 v[62:65], v[140:143], v[184:187], v[62:65]
	v_mfma_f32_16x16x32_bf16 v[58:61], v[152:155], v[184:187], v[58:61]
	v_mfma_f32_16x16x32_bf16 v[54:57], v[140:143], v[206:209], v[54:57]
	v_mfma_f32_16x16x32_bf16 v[46:49], v[152:155], v[206:209], v[46:49]
	v_mfma_f32_16x16x32_bf16 v[38:41], v[140:143], v[214:217], v[38:41]
	v_mfma_f32_16x16x32_bf16 v[30:33], v[152:155], v[214:217], v[30:33]
	v_mfma_f32_16x16x32_bf16 v[22:25], v[140:143], v[222:225], v[22:25]
	v_mfma_f32_16x16x32_bf16 v[14:17], v[152:155], v[222:225], v[14:17]
	v_mfma_f32_16x16x32_bf16 v[62:65], v[148:151], v[202:205], v[62:65]
	v_mfma_f32_16x16x32_bf16 v[58:61], v[156:159], v[202:205], v[58:61]
	v_mfma_f32_16x16x32_bf16 v[54:57], v[148:151], v[210:213], v[54:57]
	v_mfma_f32_16x16x32_bf16 v[46:49], v[156:159], v[210:213], v[46:49]
	v_mfma_f32_16x16x32_bf16 v[38:41], v[148:151], v[218:221], v[38:41]
	v_mfma_f32_16x16x32_bf16 v[30:33], v[156:159], v[218:221], v[30:33]
	v_mfma_f32_16x16x32_bf16 v[22:25], v[148:151], v[226:229], v[22:25]
	v_mfma_f32_16x16x32_bf16 v[14:17], v[156:159], v[226:229], v[14:17]
	v_mfma_f32_16x16x32_bf16 v[50:53], v[160:163], v[184:187], v[50:53]
	v_mfma_f32_16x16x32_bf16 v[42:45], v[168:171], v[184:187], v[42:45]
	v_mfma_f32_16x16x32_bf16 v[34:37], v[160:163], v[206:209], v[34:37]
	v_mfma_f32_16x16x32_bf16 v[26:29], v[168:171], v[206:209], v[26:29]
	v_mfma_f32_16x16x32_bf16 v[18:21], v[160:163], v[214:217], v[18:21]
	v_mfma_f32_16x16x32_bf16 v[10:13], v[168:171], v[214:217], v[10:13]
	v_mfma_f32_16x16x32_bf16 v[6:9], v[160:163], v[222:225], v[6:9]
	v_mfma_f32_16x16x32_bf16 v[2:5], v[168:171], v[222:225], v[2:5]
	v_mfma_f32_16x16x32_bf16 v[50:53], v[164:167], v[202:205], v[50:53]
	v_mfma_f32_16x16x32_bf16 v[42:45], v[172:175], v[202:205], v[42:45]
	v_mfma_f32_16x16x32_bf16 v[34:37], v[164:167], v[210:213], v[34:37]
	v_mfma_f32_16x16x32_bf16 v[26:29], v[172:175], v[210:213], v[26:29]
	v_mfma_f32_16x16x32_bf16 v[18:21], v[164:167], v[218:221], v[18:21]
	v_mfma_f32_16x16x32_bf16 v[10:13], v[172:175], v[218:221], v[10:13]
	v_mfma_f32_16x16x32_bf16 v[6:9], v[164:167], v[226:229], v[6:9]
	v_mfma_f32_16x16x32_bf16 v[2:5], v[172:175], v[226:229], v[2:5]
	s_setprio 0
	s_barrier
	s_add_i32 s40, s40, 2
	s_add_u32 s20, s20, 0x100
	s_addc_u32 s21, s21, 0
	s_add_u32 s38, s38, 0x100
	s_addc_u32 s39, s39, 0
	s_cmp_gt_u32 s40, 29
	s_cbranch_scc0 .LBB0_496
	s_and_b64 vcc, exec, s[4:5]
	s_cbranch_vccz .LBB0_499
	s_barrier
